# P0 weight transposition rewritten by hand: register-only 64x64 transposition with dwordx4 loads, double-buffered, 2 waves per workgroup convert while 6 start the x cast
# speedup vs baseline: 1.0127x; 1.0127x over previous
; #define LAS __attribute__((address_space(3)))
; __device__ __forceinline__ void p0_transpose_item(const float* W, int K, int N, bf16* WT, int item, bool inproj, const float* gk, LAS float* scr, int lane) {
;     const int nblk = N / 64, kb = item / nblk, nb = item % nblk, k0 = 64 * kb, n0 = 64 * nb;
;     int sc = n0 + lane, cl = lane;
;     if (inproj && n0 < 3072) {
;         const int sec = n0 >> 10;
;         if (sec == 1) sc = n0 + 1024 + lane;
;         else { const int hb = (sec == 0 ? 1024 : 0) + (n0 & 1023 & ~127); sc = hb + ((n0 & 127) >> 1) + (lane & 31) + 64 * (lane >> 5); cl = 2 * (lane & 31) + (lane >> 5); }
;     }
;     const GAS1 float* src = (const GAS1 float*)(W + (size_t)k0 * N + sc);
;     float tv[64];
; #pragma unroll
;     for (int kk = 0; kk < 64; ++kk) tv[kk] = src[(size_t)kk * N];
; #pragma unroll
;     for (int kk = 0; kk < 64; ++kk) scr[kk * 65 + cl] = tv[kk];
;     LDS_WAIT(); asm volatile("" ::: "memory");
;     const int c = lane >> 3;
;     f32x4 g0 = (f32x4){1.f, 1.f, 1.f, 1.f}, g1 = g0;
;     if (gk) { g0 = *(const f32x4*)(gk + k0 + 8 * c); g1 = *(const f32x4*)(gk + k0 + 8 * c + 4); }
; #pragma unroll
;     for (int j = 0; j < 8; ++j) { const int n = (lane & 7) + 8 * j; const LAS float* s = scr + (8 * c) * 65 + n;
;         v4u o; o.x = pk2(s[0 * 65] * g0.x, s[1 * 65] * g0.y); o.y = pk2(s[2 * 65] * g0.z, s[3 * 65] * g0.w); o.z = pk2(s[4 * 65] * g1.x, s[5 * 65] * g1.y); o.w = pk2(s[6 * 65] * g1.z, s[7 * 65] * g1.w);
;         *(GAS1 v4u*)(WT + (size_t)(n0 + n) * K + k0 + 8 * c) = o; }
; __global__ void __launch_bounds__(NWAVES * 64, 2) hybrid_fwd(Args a) {
;     ...
;         for (int it = gw; it < DEPTH * PER_L; it += NGW) {
;             const int l = it / PER_L; int r = it % PER_L;
;             if (r < I_IN) { p0_transpose_item(a.w_in + (size_t)l * DM * INW, DM, INW, Wi + (size_t)l * INW * DM, r, true, a.norm1_g + l * DM, scr, lane); continue; } r -= I_IN;
;             if (r < I_OUT) { p0_transpose_item(a.w_out + (size_t)l * DM * DM, DM, DM, Wo + (size_t)l * DM * DM, r, false, nullptr, scr, lane); continue; } r -= I_OUT;
;             if (r < I_UP) { p0_transpose_item(a.w_up + (size_t)l * DM * DFF, DM, DFF, Wu + (size_t)l * DFF * DM, r, false, a.norm2_g + l * DM, scr, lane); continue; } r -= I_UP;
;             p0_transpose_item(a.w_down + (size_t)l * DFF * DM, DFF, DM, Wd + (size_t)l * DM * DFF, r, false, nullptr, scr, lane);
.LBB0_8:
	v_writelane_b32 v252, s20, 5
	s_nop 1
	v_writelane_b32 v252, s21, 6
	v_writelane_b32 v252, s22, 7
	v_writelane_b32 v252, s23, 8
	v_writelane_b32 v252, s24, 9
	v_writelane_b32 v252, s25, 10
	v_writelane_b32 v252, s26, 11
	v_writelane_b32 v252, s27, 12
	v_writelane_b32 v252, s16, 13
	s_nop 1
	v_writelane_b32 v252, s17, 14
	v_writelane_b32 v252, s18, 15
	v_writelane_b32 v252, s19, 16
	s_load_dwordx16 s[8:23], s[0:1], 0x0
	s_waitcnt lgkmcnt(0)
	v_writelane_b32 v252, s8, 17
	s_nop 1
	v_writelane_b32 v252, s9, 18
	v_writelane_b32 v252, s10, 19
	v_writelane_b32 v252, s11, 20
	v_writelane_b32 v252, s12, 21
	v_writelane_b32 v252, s13, 22
	v_writelane_b32 v252, s14, 23
	v_writelane_b32 v252, s15, 24
	v_writelane_b32 v252, s16, 25
	v_writelane_b32 v252, s17, 26
	v_writelane_b32 v252, s18, 27
	v_writelane_b32 v252, s19, 28
	v_writelane_b32 v252, s20, 29
	v_writelane_b32 v252, s21, 30
	v_writelane_b32 v252, s22, 31
	v_writelane_b32 v252, s23, 32
	v_writelane_b32 v252, s6, 33
	s_lshl_b32 s0, s6, 3
	s_lshr_b32 s9, s4, 6
	v_writelane_b32 v252, s7, 34
	v_writelane_b32 v252, s0, 35
	v_writelane_b32 v252, s4, 36
	s_lshl_b32 s0, s94, 3
	v_writelane_b32 v252, s9, 37
	s_add_i32 s8, s9, s0
	s_cmpk_gt_i32 s8, 0x5bff
	v_writelane_b32 v252, s0, 38
	v_mbcnt_lo_u32_b32 v10, -1, 0
	v_mbcnt_hi_u32_b32 v10, -1, v10
	s_cbranch_scc1 .LBB0_36
	v_lshrrev_b32_e32 v20, 4, v10
	v_and_b32_e32 v21, 15, v10
	v_lshlrev_b32_e32 v22, 4, v20
	v_lshlrev_b32_e32 v23, 4, v21
	v_and_b32_e32 v29, 7, v21
	v_lshrrev_b32_e32 v34, 3, v21
	v_lshlrev_b32_e32 v24, 4, v29
	v_lshl_add_u32 v24, v34, 8, v24
	v_lshlrev_b32_e32 v25, 2, v21
	v_lshl_add_u32 v26, v29, 3, v34
	v_lshlrev_b32_e32 v27, 3, v20
	v_lshlrev_b32_e32 v28, 5, v20
	v_readlane_b32 s11, v252, 35
	s_mov_b32 s10, s8
	s_lshr_b32 s11, s11, 2
	s_lshl_b32 s10, s94, 1
	s_add_u32 s10, s10, s9
	s_cmp_ge_u32 s9, 2
	s_cbranch_scc1 .Lp0_done
	s_cmp_ge_u32 s10, 11776
	s_cselect_b32 s0, 1, 0
	s_cselect_b32 s1, 11776, 0
	s_sub_u32 s1, s10, s1
	s_lshl_b32 s7, s0, 13
	s_mov_b32 s26, 0
	s_cmp_lt_u32 s1, 2560
	s_cbranch_scc1 .Lp0_in_A0
	s_cmp_lt_u32 s1, 3584
	s_cbranch_scc1 .Lp0_out_A0
	s_cmp_lt_u32 s1, 7680
	s_cbranch_scc1 .Lp0_up_A0
	s_sub_u32 s1, s1, 7680
	s_and_b32 s4, s1, 7
	s_lshr_b32 s5, s1, 3
	s_lshr_b32 s2, s5, 2
	s_and_b32 s3, s5, 3
	s_lshl_b32 s2, s2, 0
	s_lshl_b32 s3, s3, 3
	s_lshr_b32 s5, s4, 3
	s_and_b32 s4, s4, 7
	s_add_u32 s2, s2, s5
	s_add_u32 s3, s3, s4
	v_readlane_b32 s4, v252, 9
	v_readlane_b32 s5, v252, 10
	s_mul_i32 s6, s0, 0x4000000
	s_mul_i32 s12, s2, 0x80000
	s_lshl_b32 s13, s3, 8
	s_add_u32 s12, s12, s13
	s_add_u32 s12, s12, s6
	s_add_u32 s16, s4, s12
	s_addc_u32 s17, s5, 0
	s_mov_b32 s18, 0x2000
	s_mov_b32 s19, 0x32000
	s_mul_i32 s6, s0, 0x2000000
	s_add_u32 s6, s6, 0x7800000
	s_lshl_b32 s12, s3, 20
	s_lshl_b32 s13, s2, 7
	s_add_u32 s12, s12, s13
	s_add_u32 s12, s12, s6
	s_mov_b32 s27, 0x4000
	s_mov_b32 s22, 0x4000
	s_mov_b32 s23, 0
	v_readlane_b32 s24, v252, 19
	v_readlane_b32 s25, v252, 20
	s_branch .Lp0_dec_done_A0
.Lp0_in_A0:
	s_and_b32 s4, s1, 7
	s_lshr_b32 s5, s1, 3
	s_mul_i32 s2, s5, 205
	s_lshr_b32 s2, s2, 11
	s_mul_i32 s3, s2, 10
	s_sub_u32 s3, s5, s3
	s_lshl_b32 s2, s2, 0
	s_lshl_b32 s3, s3, 3
	s_lshr_b32 s5, s4, 3
	s_and_b32 s4, s4, 7
	s_add_u32 s2, s2, s5
	s_add_u32 s3, s3, s4
	s_lshl_b32 s13, s3, 6
	s_and_b32 s4, s13, 0x380
	s_and_b32 s5, s13, 64
	s_lshr_b32 s5, s5, 1
	s_add_u32 s4, s4, s5
	s_mov_b32 s12, s13
	s_cmp_ge_u32 s13, 3072
	s_cbranch_scc1 .Lp0_in_cb_A0
	s_add_u32 s12, s13, 1024
	s_lshr_b32 s5, s13, 10
	s_cmp_eq_u32 s5, 1
	s_cbranch_scc1 .Lp0_in_cb_A0
	s_mov_b32 s26, 1
	s_mov_b32 s12, s4
	s_cmp_eq_u32 s5, 2
	s_cbranch_scc1 .Lp0_in_cb_A0
	s_add_u32 s12, s4, 1024
.Lp0_in_cb_A0:
	v_readlane_b32 s4, v252, 21
	v_readlane_b32 s5, v252, 22
	s_mul_i32 s6, s0, 0x2800000
	s_mul_i32 s14, s2, 0x140000
	s_lshl_b32 s12, s12, 2
	s_add_u32 s12, s12, s14
	s_add_u32 s12, s12, s6
	s_add_u32 s16, s4, s12
	s_addc_u32 s17, s5, 0
	s_mov_b32 s18, 0x5000
	s_mov_b32 s19, 0x7d000
	s_mul_i32 s6, s0, 0x1400000
	s_lshl_b32 s12, s13, 12
	s_lshl_b32 s13, s2, 7
	s_add_u32 s12, s12, s13
	s_add_u32 s12, s12, s6
	s_mov_b32 s27, 0x1000
	s_lshl_b32 s22, s26, 12
	s_add_u32 s22, s22, 0x1000
	s_mov_b32 s23, 1
	v_readlane_b32 s4, v252, 19
	v_readlane_b32 s5, v252, 20
	s_lshl_b32 s14, s2, 8
	s_add_u32 s14, s14, s7
	s_add_u32 s24, s4, s14
	s_addc_u32 s25, s5, 0
	s_branch .Lp0_dec_done_A0
.Lp0_out_A0:
	s_sub_u32 s1, s1, 2560
	s_and_b32 s4, s1, 7
	s_lshr_b32 s5, s1, 3
	s_lshr_b32 s2, s5, 2
	s_and_b32 s3, s5, 3
	s_lshl_b32 s2, s2, 0
	s_lshl_b32 s3, s3, 3
	s_lshr_b32 s5, s4, 3
	s_and_b32 s4, s4, 7
	s_add_u32 s2, s2, s5
	s_add_u32 s3, s3, s4
	v_readlane_b32 s4, v252, 31
	v_readlane_b32 s5, v252, 32
	s_mul_i32 s6, s0, 0x1000000
	s_mul_i32 s12, s2, 0x80000
	s_lshl_b32 s13, s3, 8
	s_add_u32 s12, s12, s13
	s_add_u32 s12, s12, s6
	s_add_u32 s16, s4, s12
	s_addc_u32 s17, s5, 0
	s_mov_b32 s18, 0x2000
	s_mov_b32 s19, 0x32000
	s_mul_i32 s6, s0, 0x800000
	s_add_u32 s6, s6, 0x2800000
	s_lshl_b32 s12, s3, 18
	s_lshl_b32 s13, s2, 7
	s_add_u32 s12, s12, s13
	s_add_u32 s12, s12, s6
	s_mov_b32 s27, 0x1000
	s_mov_b32 s22, 0x1000
	s_mov_b32 s23, 0
	v_readlane_b32 s24, v252, 19
	v_readlane_b32 s25, v252, 20
	s_branch .Lp0_dec_done_A0
; #define LAS __attribute__((address_space(3)))
; #define GAS1 __attribute__((address_space(1)))
; #define LDS_WAIT() asm volatile("s_waitcnt lgkmcnt(0)" ::: "memory")
; __device__ __forceinline__ unsigned pk2(float lo, float hi) { return pg8::cvt_pk_bf16(lo, hi); }
; __device__ __forceinline__ void p0_transpose_item(const float* W, int K, int N, bf16* WT, int item, bool inproj, const float* gk, LAS float* scr, int lane) {
;     const int nblk = N / 64, kb = item / nblk, nb = item % nblk, k0 = 64 * kb, n0 = 64 * nb;
;     int sc = n0 + lane, cl = lane;
;     if (inproj && n0 < 3072) {
;         const int sec = n0 >> 10;
;         if (sec == 1) sc = n0 + 1024 + lane;
;         else { const int hb = (sec == 0 ? 1024 : 0) + (n0 & 1023 & ~127); sc = hb + ((n0 & 127) >> 1) + (lane & 31) + 64 * (lane >> 5); cl = 2 * (lane & 31) + (lane >> 5); }
;     }
;     const GAS1 float* src = (const GAS1 float*)(W + (size_t)k0 * N + sc);
;     float tv[64];
; #pragma unroll
;     for (int kk = 0; kk < 64; ++kk) tv[kk] = src[(size_t)kk * N];
; #pragma unroll
;     for (int kk = 0; kk < 64; ++kk) scr[kk * 65 + cl] = tv[kk];
;     LDS_WAIT(); asm volatile("" ::: "memory");
;     const int c = lane >> 3;
;     f32x4 g0 = (f32x4){1.f, 1.f, 1.f, 1.f}, g1 = g0;
;     if (gk) { g0 = *(const f32x4*)(gk + k0 + 8 * c); g1 = *(const f32x4*)(gk + k0 + 8 * c + 4); }
; #pragma unroll
;     for (int j = 0; j < 8; ++j) { const int n = (lane & 7) + 8 * j; const LAS float* s = scr + (8 * c) * 65 + n;
;         v4u o; o.x = pk2(s[0 * 65] * g0.x, s[1 * 65] * g0.y); o.y = pk2(s[2 * 65] * g0.z, s[3 * 65] * g0.w); o.z = pk2(s[4 * 65] * g1.x, s[5 * 65] * g1.y); o.w = pk2(s[6 * 65] * g1.z, s[7 * 65] * g1.w);
;         *(GAS1 v4u*)(WT + (size_t)(n0 + n) * K + k0 + 8 * c) = o; }
.Lp0_up_A0:
	s_sub_u32 s1, s1, 3584
	s_and_b32 s4, s1, 7
	s_lshr_b32 s5, s1, 3
	s_lshr_b32 s2, s5, 4
	s_and_b32 s3, s5, 15
	s_lshl_b32 s2, s2, 0
	s_lshl_b32 s3, s3, 3
	s_lshr_b32 s5, s4, 3
	s_and_b32 s4, s4, 7
	s_add_u32 s2, s2, s5
	s_add_u32 s3, s3, s4
	v_readlane_b32 s4, v252, 7
	v_readlane_b32 s5, v252, 8
	s_mul_i32 s6, s0, 0x4000000
	s_lshl_b32 s12, s2, 21
	s_lshl_b32 s13, s3, 8
	s_add_u32 s12, s12, s13
	s_add_u32 s12, s12, s6
	s_add_u32 s16, s4, s12
	s_addc_u32 s17, s5, 0
	s_mov_b32 s18, 0x8000
	s_mov_b32 s19, 0xc8000
	s_mul_i32 s6, s0, 0x2000000
	s_add_u32 s6, s6, 0x3800000
	s_lshl_b32 s12, s3, 18
	s_lshl_b32 s13, s2, 7
	s_add_u32 s12, s12, s13
	s_add_u32 s12, s12, s6
	s_mov_b32 s27, 0x1000
	s_mov_b32 s22, 0x1000
	s_mov_b32 s23, 1
	v_readlane_b32 s4, v252, 5
	v_readlane_b32 s5, v252, 6
	s_lshl_b32 s14, s2, 8
	s_add_u32 s14, s14, s7
	s_add_u32 s24, s4, s14
	s_addc_u32 s25, s5, 0
.Lp0_dec_done_A0:
	v_readlane_b32 s4, v252, 15
	v_readlane_b32 s5, v252, 16
	s_add_u32 s20, s4, s12
	s_addc_u32 s21, s5, 0
	s_cmp_eq_u32 s26, 0
	s_cselect_b64 vcc, -1, 0
	v_mul_u32_u24_e32 v30, s18, v27
	v_cndmask_b32_e32 v35, v24, v23, vcc
	v_cndmask_b32_e32 v36, v26, v25, vcc
	v_add_u32_e32 v30, v30, v35
	v_mad_u32_u24 v31, v36, s27, v22
	global_load_dwordx4 v[104:107], v28, s[24:25]
	global_load_dwordx4 v[108:111], v28, s[24:25] offset:16
	global_load_dwordx4 v[112:115], v28, s[24:25] offset:128
	global_load_dwordx4 v[116:119], v28, s[24:25] offset:144
	global_load_dwordx4 v[40:43], v30, s[16:17]
	s_add_u32 s16, s16, s18
	s_addc_u32 s17, s17, 0
	global_load_dwordx4 v[44:47], v30, s[16:17]
	s_add_u32 s16, s16, s18
	s_addc_u32 s17, s17, 0
	global_load_dwordx4 v[48:51], v30, s[16:17]
	s_add_u32 s16, s16, s18
	s_addc_u32 s17, s17, 0
	global_load_dwordx4 v[52:55], v30, s[16:17]
	s_add_u32 s16, s16, s18
	s_addc_u32 s17, s17, 0
	global_load_dwordx4 v[56:59], v30, s[16:17]
	s_add_u32 s16, s16, s18
	s_addc_u32 s17, s17, 0
	global_load_dwordx4 v[60:63], v30, s[16:17]
	s_add_u32 s16, s16, s18
	s_addc_u32 s17, s17, 0
	global_load_dwordx4 v[64:67], v30, s[16:17]
	s_add_u32 s16, s16, s18
	s_addc_u32 s17, s17, 0
	global_load_dwordx4 v[68:71], v30, s[16:17]
	s_add_u32 s16, s16, s19
	s_addc_u32 s17, s17, 0
	global_load_dwordx4 v[72:75], v30, s[16:17]
	s_add_u32 s16, s16, s18
	s_addc_u32 s17, s17, 0
	global_load_dwordx4 v[76:79], v30, s[16:17]
	s_add_u32 s16, s16, s18
	s_addc_u32 s17, s17, 0
	global_load_dwordx4 v[80:83], v30, s[16:17]
	s_add_u32 s16, s16, s18
	s_addc_u32 s17, s17, 0
	global_load_dwordx4 v[84:87], v30, s[16:17]
	s_add_u32 s16, s16, s18
	s_addc_u32 s17, s17, 0
	global_load_dwordx4 v[88:91], v30, s[16:17]
	s_add_u32 s16, s16, s18
	s_addc_u32 s17, s17, 0
	global_load_dwordx4 v[92:95], v30, s[16:17]
	s_add_u32 s16, s16, s18
	s_addc_u32 s17, s17, 0
	global_load_dwordx4 v[96:99], v30, s[16:17]
	s_add_u32 s16, s16, s18
	s_addc_u32 s17, s17, 0
	global_load_dwordx4 v[100:103], v30, s[16:17]
	s_add_u32 s10, s10, s11
	s_cmp_lt_u32 s10, 23552
	s_cselect_b32 s59, 1, 0
	s_cbranch_scc0 .Lp0_last_first
	s_cmp_ge_u32 s10, 11776
	s_cselect_b32 s0, 1, 0
	s_cselect_b32 s1, 11776, 0
	s_sub_u32 s1, s10, s1
	s_lshl_b32 s7, s0, 13
	s_mov_b32 s50, 0
	s_cmp_lt_u32 s1, 2560
	s_cbranch_scc1 .Lp0_in_B1
	s_cmp_lt_u32 s1, 3584
	s_cbranch_scc1 .Lp0_out_B1
	s_cmp_lt_u32 s1, 7680
	s_cbranch_scc1 .Lp0_up_B1
	s_sub_u32 s1, s1, 7680
	s_and_b32 s4, s1, 7
	s_lshr_b32 s5, s1, 3
	s_lshr_b32 s2, s5, 2
	s_and_b32 s3, s5, 3
	s_lshl_b32 s2, s2, 0
	s_lshl_b32 s3, s3, 3
	s_lshr_b32 s5, s4, 3
	s_and_b32 s4, s4, 7
	s_add_u32 s2, s2, s5
	s_add_u32 s3, s3, s4
	v_readlane_b32 s4, v252, 9
	v_readlane_b32 s5, v252, 10
	s_mul_i32 s6, s0, 0x4000000
	s_mul_i32 s12, s2, 0x80000
	s_lshl_b32 s13, s3, 8
	s_add_u32 s12, s12, s13
	s_add_u32 s12, s12, s6
	s_add_u32 s40, s4, s12
	s_addc_u32 s41, s5, 0
	s_mov_b32 s42, 0x2000
	s_mov_b32 s43, 0x32000
	s_mul_i32 s6, s0, 0x2000000
	s_add_u32 s6, s6, 0x7800000
	s_lshl_b32 s12, s3, 20
	s_lshl_b32 s13, s2, 7
	s_add_u32 s12, s12, s13
	s_add_u32 s12, s12, s6
	s_mov_b32 s51, 0x4000
	s_mov_b32 s46, 0x4000
	s_mov_b32 s47, 0
	v_readlane_b32 s48, v252, 19
	v_readlane_b32 s49, v252, 20
	s_branch .Lp0_dec_done_B1
.Lp0_in_B1:
	s_and_b32 s4, s1, 7
	s_lshr_b32 s5, s1, 3
	s_mul_i32 s2, s5, 205
	s_lshr_b32 s2, s2, 11
	s_mul_i32 s3, s2, 10
	s_sub_u32 s3, s5, s3
	s_lshl_b32 s2, s2, 0
	s_lshl_b32 s3, s3, 3
	s_lshr_b32 s5, s4, 3
	s_and_b32 s4, s4, 7
	s_add_u32 s2, s2, s5
	s_add_u32 s3, s3, s4
	s_lshl_b32 s13, s3, 6
	s_and_b32 s4, s13, 0x380
	s_and_b32 s5, s13, 64
	s_lshr_b32 s5, s5, 1
	s_add_u32 s4, s4, s5
	s_mov_b32 s12, s13
	s_cmp_ge_u32 s13, 3072
	s_cbranch_scc1 .Lp0_in_cb_B1
	s_add_u32 s12, s13, 1024
	s_lshr_b32 s5, s13, 10
	s_cmp_eq_u32 s5, 1
	s_cbranch_scc1 .Lp0_in_cb_B1
	s_mov_b32 s50, 1
	s_mov_b32 s12, s4
	s_cmp_eq_u32 s5, 2
	s_cbranch_scc1 .Lp0_in_cb_B1
	s_add_u32 s12, s4, 1024
; #define LAS __attribute__((address_space(3)))
; #define GAS1 __attribute__((address_space(1)))
; #define LDS_WAIT() asm volatile("s_waitcnt lgkmcnt(0)" ::: "memory")
; __device__ __forceinline__ unsigned pk2(float lo, float hi) { return pg8::cvt_pk_bf16(lo, hi); }
; __device__ __forceinline__ void p0_transpose_item(const float* W, int K, int N, bf16* WT, int item, bool inproj, const float* gk, LAS float* scr, int lane) {
;     const int nblk = N / 64, kb = item / nblk, nb = item % nblk, k0 = 64 * kb, n0 = 64 * nb;
;     int sc = n0 + lane, cl = lane;
;     if (inproj && n0 < 3072) {
;         const int sec = n0 >> 10;
;         if (sec == 1) sc = n0 + 1024 + lane;
;         else { const int hb = (sec == 0 ? 1024 : 0) + (n0 & 1023 & ~127); sc = hb + ((n0 & 127) >> 1) + (lane & 31) + 64 * (lane >> 5); cl = 2 * (lane & 31) + (lane >> 5); }
;     }
;     const GAS1 float* src = (const GAS1 float*)(W + (size_t)k0 * N + sc);
;     float tv[64];
; #pragma unroll
;     for (int kk = 0; kk < 64; ++kk) tv[kk] = src[(size_t)kk * N];
; #pragma unroll
;     for (int kk = 0; kk < 64; ++kk) scr[kk * 65 + cl] = tv[kk];
;     LDS_WAIT(); asm volatile("" ::: "memory");
;     const int c = lane >> 3;
;     f32x4 g0 = (f32x4){1.f, 1.f, 1.f, 1.f}, g1 = g0;
;     if (gk) { g0 = *(const f32x4*)(gk + k0 + 8 * c); g1 = *(const f32x4*)(gk + k0 + 8 * c + 4); }
; #pragma unroll
;     for (int j = 0; j < 8; ++j) { const int n = (lane & 7) + 8 * j; const LAS float* s = scr + (8 * c) * 65 + n;
;         v4u o; o.x = pk2(s[0 * 65] * g0.x, s[1 * 65] * g0.y); o.y = pk2(s[2 * 65] * g0.z, s[3 * 65] * g0.w); o.z = pk2(s[4 * 65] * g1.x, s[5 * 65] * g1.y); o.w = pk2(s[6 * 65] * g1.z, s[7 * 65] * g1.w);
;         *(GAS1 v4u*)(WT + (size_t)(n0 + n) * K + k0 + 8 * c) = o; }
.Lp0_in_cb_B1:
	v_readlane_b32 s4, v252, 21
	v_readlane_b32 s5, v252, 22
	s_mul_i32 s6, s0, 0x2800000
	s_mul_i32 s14, s2, 0x140000
	s_lshl_b32 s12, s12, 2
	s_add_u32 s12, s12, s14
	s_add_u32 s12, s12, s6
	s_add_u32 s40, s4, s12
	s_addc_u32 s41, s5, 0
	s_mov_b32 s42, 0x5000
	s_mov_b32 s43, 0x7d000
	s_mul_i32 s6, s0, 0x1400000
	s_lshl_b32 s12, s13, 12
	s_lshl_b32 s13, s2, 7
	s_add_u32 s12, s12, s13
	s_add_u32 s12, s12, s6
	s_mov_b32 s51, 0x1000
	s_lshl_b32 s46, s50, 12
	s_add_u32 s46, s46, 0x1000
	s_mov_b32 s47, 1
	v_readlane_b32 s4, v252, 19
	v_readlane_b32 s5, v252, 20
	s_lshl_b32 s14, s2, 8
	s_add_u32 s14, s14, s7
	s_add_u32 s48, s4, s14
	s_addc_u32 s49, s5, 0
	s_branch .Lp0_dec_done_B1
.Lp0_out_B1:
	s_sub_u32 s1, s1, 2560
	s_and_b32 s4, s1, 7
	s_lshr_b32 s5, s1, 3
	s_lshr_b32 s2, s5, 2
	s_and_b32 s3, s5, 3
	s_lshl_b32 s2, s2, 0
	s_lshl_b32 s3, s3, 3
	s_lshr_b32 s5, s4, 3
	s_and_b32 s4, s4, 7
	s_add_u32 s2, s2, s5
	s_add_u32 s3, s3, s4
	v_readlane_b32 s4, v252, 31
	v_readlane_b32 s5, v252, 32
	s_mul_i32 s6, s0, 0x1000000
	s_mul_i32 s12, s2, 0x80000
	s_lshl_b32 s13, s3, 8
	s_add_u32 s12, s12, s13
	s_add_u32 s12, s12, s6
	s_add_u32 s40, s4, s12
	s_addc_u32 s41, s5, 0
	s_mov_b32 s42, 0x2000
	s_mov_b32 s43, 0x32000
	s_mul_i32 s6, s0, 0x800000
	s_add_u32 s6, s6, 0x2800000
	s_lshl_b32 s12, s3, 18
	s_lshl_b32 s13, s2, 7
	s_add_u32 s12, s12, s13
	s_add_u32 s12, s12, s6
	s_mov_b32 s51, 0x1000
	s_mov_b32 s46, 0x1000
	s_mov_b32 s47, 0
	v_readlane_b32 s48, v252, 19
	v_readlane_b32 s49, v252, 20
	s_branch .Lp0_dec_done_B1
.Lp0_up_B1:
	s_sub_u32 s1, s1, 3584
	s_and_b32 s4, s1, 7
	s_lshr_b32 s5, s1, 3
	s_lshr_b32 s2, s5, 4
	s_and_b32 s3, s5, 15
	s_lshl_b32 s2, s2, 0
	s_lshl_b32 s3, s3, 3
	s_lshr_b32 s5, s4, 3
	s_and_b32 s4, s4, 7
	s_add_u32 s2, s2, s5
	s_add_u32 s3, s3, s4
	v_readlane_b32 s4, v252, 7
	v_readlane_b32 s5, v252, 8
	s_mul_i32 s6, s0, 0x4000000
	s_lshl_b32 s12, s2, 21
	s_lshl_b32 s13, s3, 8
	s_add_u32 s12, s12, s13
	s_add_u32 s12, s12, s6
	s_add_u32 s40, s4, s12
	s_addc_u32 s41, s5, 0
	s_mov_b32 s42, 0x8000
	s_mov_b32 s43, 0xc8000
	s_mul_i32 s6, s0, 0x2000000
	s_add_u32 s6, s6, 0x3800000
	s_lshl_b32 s12, s3, 18
	s_lshl_b32 s13, s2, 7
	s_add_u32 s12, s12, s13
	s_add_u32 s12, s12, s6
	s_mov_b32 s51, 0x1000
	s_mov_b32 s46, 0x1000
	s_mov_b32 s47, 1
	v_readlane_b32 s4, v252, 5
	v_readlane_b32 s5, v252, 6
	s_lshl_b32 s14, s2, 8
	s_add_u32 s14, s14, s7
	s_add_u32 s48, s4, s14
	s_addc_u32 s49, s5, 0
.Lp0_dec_done_B1:
	v_readlane_b32 s4, v252, 15
	v_readlane_b32 s5, v252, 16
	s_add_u32 s44, s4, s12
	s_addc_u32 s45, s5, 0
	s_cmp_eq_u32 s50, 0
	s_cselect_b64 vcc, -1, 0
	v_mul_u32_u24_e32 v32, s42, v27
	v_cndmask_b32_e32 v35, v24, v23, vcc
	v_cndmask_b32_e32 v36, v26, v25, vcc
	v_add_u32_e32 v32, v32, v35
	v_mad_u32_u24 v33, v36, s51, v22
	global_load_dwordx4 v[184:187], v28, s[48:49]
	global_load_dwordx4 v[188:191], v28, s[48:49] offset:16
	global_load_dwordx4 v[192:195], v28, s[48:49] offset:128
	global_load_dwordx4 v[196:199], v28, s[48:49] offset:144
	global_load_dwordx4 v[120:123], v32, s[40:41]
	s_add_u32 s40, s40, s42
	s_addc_u32 s41, s41, 0
	global_load_dwordx4 v[124:127], v32, s[40:41]
	s_add_u32 s40, s40, s42
	s_addc_u32 s41, s41, 0
	global_load_dwordx4 v[128:131], v32, s[40:41]
	s_add_u32 s40, s40, s42
	s_addc_u32 s41, s41, 0
	global_load_dwordx4 v[132:135], v32, s[40:41]
	s_add_u32 s40, s40, s42
	s_addc_u32 s41, s41, 0
	global_load_dwordx4 v[136:139], v32, s[40:41]
	s_add_u32 s40, s40, s42
	s_addc_u32 s41, s41, 0
	global_load_dwordx4 v[140:143], v32, s[40:41]
	s_add_u32 s40, s40, s42
	s_addc_u32 s41, s41, 0
	global_load_dwordx4 v[144:147], v32, s[40:41]
	s_add_u32 s40, s40, s42
	s_addc_u32 s41, s41, 0
	global_load_dwordx4 v[148:151], v32, s[40:41]
	s_add_u32 s40, s40, s43
	s_addc_u32 s41, s41, 0
	global_load_dwordx4 v[152:155], v32, s[40:41]
	s_add_u32 s40, s40, s42
	s_addc_u32 s41, s41, 0
	global_load_dwordx4 v[156:159], v32, s[40:41]
	s_add_u32 s40, s40, s42
	s_addc_u32 s41, s41, 0
	global_load_dwordx4 v[160:163], v32, s[40:41]
	s_add_u32 s40, s40, s42
	s_addc_u32 s41, s41, 0
	global_load_dwordx4 v[164:167], v32, s[40:41]
	s_add_u32 s40, s40, s42
	s_addc_u32 s41, s41, 0
	global_load_dwordx4 v[168:171], v32, s[40:41]
	s_add_u32 s40, s40, s42
	s_addc_u32 s41, s41, 0
	global_load_dwordx4 v[172:175], v32, s[40:41]
	s_add_u32 s40, s40, s42
	s_addc_u32 s41, s41, 0
	global_load_dwordx4 v[176:179], v32, s[40:41]
	s_add_u32 s40, s40, s42
	s_addc_u32 s41, s41, 0
	global_load_dwordx4 v[180:183], v32, s[40:41]
	s_waitcnt vmcnt(20)
	s_branch .Lp0_go_first

; #define LAS __attribute__((address_space(3)))
; #define GAS1 __attribute__((address_space(1)))
; #define LDS_WAIT() asm volatile("s_waitcnt lgkmcnt(0)" ::: "memory")
; __device__ __forceinline__ unsigned pk2(float lo, float hi) { return pg8::cvt_pk_bf16(lo, hi); }
; __device__ __forceinline__ void p0_transpose_item(const float* W, int K, int N, bf16* WT, int item, bool inproj, const float* gk, LAS float* scr, int lane) {
;     ...
; #pragma unroll
;     for (int kk = 0; kk < 64; ++kk) tv[kk] = src[(size_t)kk * N];
; #pragma unroll
;     for (int kk = 0; kk < 64; ++kk) scr[kk * 65 + cl] = tv[kk];
;     LDS_WAIT(); asm volatile("" ::: "memory");
;     const int c = lane >> 3;
;     f32x4 g0 = (f32x4){1.f, 1.f, 1.f, 1.f}, g1 = g0;
;     if (gk) { g0 = *(const f32x4*)(gk + k0 + 8 * c); g1 = *(const f32x4*)(gk + k0 + 8 * c + 4); }
; #pragma unroll
;     for (int j = 0; j < 8; ++j) { const int n = (lane & 7) + 8 * j; const LAS float* s = scr + (8 * c) * 65 + n;
;         v4u o; o.x = pk2(s[0 * 65] * g0.x, s[1 * 65] * g0.y); o.y = pk2(s[2 * 65] * g0.z, s[3 * 65] * g0.w); o.z = pk2(s[4 * 65] * g1.x, s[5 * 65] * g1.y); o.w = pk2(s[6 * 65] * g1.z, s[7 * 65] * g1.w);
;         *(GAS1 v4u*)(WT + (size_t)(n0 + n) * K + k0 + 8 * c) = o; }
.Lp0_go_first:
	s_cmp_eq_u32 s23, 0
	s_cbranch_scc1 .Lp0_nog_A0
	v_pk_mul_f32 v[40:41], v[40:41], v[104:105] op_sel_hi:[1,0]
	v_pk_mul_f32 v[42:43], v[42:43], v[104:105] op_sel_hi:[1,0]
	v_pk_mul_f32 v[44:45], v[44:45], v[104:105] op_sel:[0,1] op_sel_hi:[1,1]
	v_pk_mul_f32 v[46:47], v[46:47], v[104:105] op_sel:[0,1] op_sel_hi:[1,1]
	v_pk_mul_f32 v[48:49], v[48:49], v[106:107] op_sel_hi:[1,0]
	v_pk_mul_f32 v[50:51], v[50:51], v[106:107] op_sel_hi:[1,0]
	v_pk_mul_f32 v[52:53], v[52:53], v[106:107] op_sel:[0,1] op_sel_hi:[1,1]
	v_pk_mul_f32 v[54:55], v[54:55], v[106:107] op_sel:[0,1] op_sel_hi:[1,1]
	v_pk_mul_f32 v[56:57], v[56:57], v[108:109] op_sel_hi:[1,0]
	v_pk_mul_f32 v[58:59], v[58:59], v[108:109] op_sel_hi:[1,0]
	v_pk_mul_f32 v[60:61], v[60:61], v[108:109] op_sel:[0,1] op_sel_hi:[1,1]
	v_pk_mul_f32 v[62:63], v[62:63], v[108:109] op_sel:[0,1] op_sel_hi:[1,1]
	v_pk_mul_f32 v[64:65], v[64:65], v[110:111] op_sel_hi:[1,0]
	v_pk_mul_f32 v[66:67], v[66:67], v[110:111] op_sel_hi:[1,0]
	v_pk_mul_f32 v[68:69], v[68:69], v[110:111] op_sel:[0,1] op_sel_hi:[1,1]
	v_pk_mul_f32 v[70:71], v[70:71], v[110:111] op_sel:[0,1] op_sel_hi:[1,1]
	v_pk_mul_f32 v[72:73], v[72:73], v[112:113] op_sel_hi:[1,0]
	v_pk_mul_f32 v[74:75], v[74:75], v[112:113] op_sel_hi:[1,0]
	v_pk_mul_f32 v[76:77], v[76:77], v[112:113] op_sel:[0,1] op_sel_hi:[1,1]
	v_pk_mul_f32 v[78:79], v[78:79], v[112:113] op_sel:[0,1] op_sel_hi:[1,1]
	v_pk_mul_f32 v[80:81], v[80:81], v[114:115] op_sel_hi:[1,0]
	v_pk_mul_f32 v[82:83], v[82:83], v[114:115] op_sel_hi:[1,0]
	v_pk_mul_f32 v[84:85], v[84:85], v[114:115] op_sel:[0,1] op_sel_hi:[1,1]
	v_pk_mul_f32 v[86:87], v[86:87], v[114:115] op_sel:[0,1] op_sel_hi:[1,1]
	v_pk_mul_f32 v[88:89], v[88:89], v[116:117] op_sel_hi:[1,0]
	v_pk_mul_f32 v[90:91], v[90:91], v[116:117] op_sel_hi:[1,0]
	v_pk_mul_f32 v[92:93], v[92:93], v[116:117] op_sel:[0,1] op_sel_hi:[1,1]
	v_pk_mul_f32 v[94:95], v[94:95], v[116:117] op_sel:[0,1] op_sel_hi:[1,1]
	v_pk_mul_f32 v[96:97], v[96:97], v[118:119] op_sel_hi:[1,0]
	v_pk_mul_f32 v[98:99], v[98:99], v[118:119] op_sel_hi:[1,0]
	v_pk_mul_f32 v[100:101], v[100:101], v[118:119] op_sel:[0,1] op_sel_hi:[1,1]
	v_pk_mul_f32 v[102:103], v[102:103], v[118:119] op_sel:[0,1] op_sel_hi:[1,1]
.Lp0_nog_A0:
	v_cvt_pk_bf16_f32 v208, v40, v44
	v_cvt_pk_bf16_f32 v209, v48, v52
	v_cvt_pk_bf16_f32 v210, v56, v60
	v_cvt_pk_bf16_f32 v211, v64, v68
	global_store_dwordx4 v31, v[208:211], s[20:21]
	v_cvt_pk_bf16_f32 v212, v72, v76
	v_cvt_pk_bf16_f32 v213, v80, v84
	v_cvt_pk_bf16_f32 v214, v88, v92
	v_cvt_pk_bf16_f32 v215, v96, v100
	global_store_dwordx4 v31, v[212:215], s[20:21] offset:64
	s_add_u32 s20, s20, s22
	s_addc_u32 s21, s21, 0
	v_cvt_pk_bf16_f32 v216, v41, v45
	v_cvt_pk_bf16_f32 v217, v49, v53
	v_cvt_pk_bf16_f32 v218, v57, v61
	v_cvt_pk_bf16_f32 v219, v65, v69
	global_store_dwordx4 v31, v[216:219], s[20:21]
	v_cvt_pk_bf16_f32 v220, v73, v77
	v_cvt_pk_bf16_f32 v221, v81, v85
	v_cvt_pk_bf16_f32 v222, v89, v93
	v_cvt_pk_bf16_f32 v223, v97, v101
	global_store_dwordx4 v31, v[220:223], s[20:21] offset:64
	s_add_u32 s20, s20, s22
	s_addc_u32 s21, s21, 0
	v_cvt_pk_bf16_f32 v224, v42, v46
	v_cvt_pk_bf16_f32 v225, v50, v54
	v_cvt_pk_bf16_f32 v226, v58, v62
	v_cvt_pk_bf16_f32 v227, v66, v70
	global_store_dwordx4 v31, v[224:227], s[20:21]
	v_cvt_pk_bf16_f32 v228, v74, v78
	v_cvt_pk_bf16_f32 v229, v82, v86
	v_cvt_pk_bf16_f32 v230, v90, v94
	v_cvt_pk_bf16_f32 v231, v98, v102
	global_store_dwordx4 v31, v[228:231], s[20:21] offset:64
	s_add_u32 s20, s20, s22
	s_addc_u32 s21, s21, 0
	v_cvt_pk_bf16_f32 v232, v43, v47
	v_cvt_pk_bf16_f32 v233, v51, v55
	v_cvt_pk_bf16_f32 v234, v59, v63
	v_cvt_pk_bf16_f32 v235, v67, v71
	global_store_dwordx4 v31, v[232:235], s[20:21]
	v_cvt_pk_bf16_f32 v236, v75, v79
	v_cvt_pk_bf16_f32 v237, v83, v87
	v_cvt_pk_bf16_f32 v238, v91, v95
	v_cvt_pk_bf16_f32 v239, v99, v103
	global_store_dwordx4 v31, v[236:239], s[20:21] offset:64
	s_cmp_eq_u32 s59, 0
	s_cbranch_scc1 .Lp0_done
.Lp0_loop:
	s_add_u32 s10, s10, s11
	s_cmp_lt_u32 s10, 23552
	s_cselect_b32 s59, 1, 0
	s_cbranch_scc0 .Lp0_last_a
	s_cmp_ge_u32 s10, 11776
	s_cselect_b32 s0, 1, 0
	s_cselect_b32 s1, 11776, 0
	s_sub_u32 s1, s10, s1
	s_lshl_b32 s7, s0, 13
	s_mov_b32 s26, 0
	s_cmp_lt_u32 s1, 2560
	s_cbranch_scc1 .Lp0_in_A2
	s_cmp_lt_u32 s1, 3584
	s_cbranch_scc1 .Lp0_out_A2
	s_cmp_lt_u32 s1, 7680
	s_cbranch_scc1 .Lp0_up_A2
	s_sub_u32 s1, s1, 7680
	s_and_b32 s4, s1, 7
	s_lshr_b32 s5, s1, 3
	s_lshr_b32 s2, s5, 2
	s_and_b32 s3, s5, 3
	s_lshl_b32 s2, s2, 0
	s_lshl_b32 s3, s3, 3
	s_lshr_b32 s5, s4, 3
	s_and_b32 s4, s4, 7
	s_add_u32 s2, s2, s5
	s_add_u32 s3, s3, s4
	v_readlane_b32 s4, v252, 9
	v_readlane_b32 s5, v252, 10
	s_mul_i32 s6, s0, 0x4000000
	s_mul_i32 s12, s2, 0x80000
	s_lshl_b32 s13, s3, 8
	s_add_u32 s12, s12, s13
	s_add_u32 s12, s12, s6
	s_add_u32 s16, s4, s12
	s_addc_u32 s17, s5, 0
	s_mov_b32 s18, 0x2000
	s_mov_b32 s19, 0x32000
	s_mul_i32 s6, s0, 0x2000000
	s_add_u32 s6, s6, 0x7800000
	s_lshl_b32 s12, s3, 20
	s_lshl_b32 s13, s2, 7
	s_add_u32 s12, s12, s13
	s_add_u32 s12, s12, s6
	s_mov_b32 s27, 0x4000
	s_mov_b32 s22, 0x4000
	s_mov_b32 s23, 0
	v_readlane_b32 s24, v252, 19
	v_readlane_b32 s25, v252, 20
	s_branch .Lp0_dec_done_A2

; #define LAS __attribute__((address_space(3)))
; #define GAS1 __attribute__((address_space(1)))
; #define LDS_WAIT() asm volatile("s_waitcnt lgkmcnt(0)" ::: "memory")
; __device__ __forceinline__ unsigned pk2(float lo, float hi) { return pg8::cvt_pk_bf16(lo, hi); }
; __device__ __forceinline__ void p0_transpose_item(const float* W, int K, int N, bf16* WT, int item, bool inproj, const float* gk, LAS float* scr, int lane) {
;     ...
; #pragma unroll
;     for (int kk = 0; kk < 64; ++kk) tv[kk] = src[(size_t)kk * N];
; #pragma unroll
;     for (int kk = 0; kk < 64; ++kk) scr[kk * 65 + cl] = tv[kk];
;     LDS_WAIT(); asm volatile("" ::: "memory");
;     const int c = lane >> 3;
;     f32x4 g0 = (f32x4){1.f, 1.f, 1.f, 1.f}, g1 = g0;
;     if (gk) { g0 = *(const f32x4*)(gk + k0 + 8 * c); g1 = *(const f32x4*)(gk + k0 + 8 * c + 4); }
; #pragma unroll
;     for (int j = 0; j < 8; ++j) { const int n = (lane & 7) + 8 * j; const LAS float* s = scr + (8 * c) * 65 + n;
;         v4u o; o.x = pk2(s[0 * 65] * g0.x, s[1 * 65] * g0.y); o.y = pk2(s[2 * 65] * g0.z, s[3 * 65] * g0.w); o.z = pk2(s[4 * 65] * g1.x, s[5 * 65] * g1.y); o.w = pk2(s[6 * 65] * g1.z, s[7 * 65] * g1.w);
;         *(GAS1 v4u*)(WT + (size_t)(n0 + n) * K + k0 + 8 * c) = o; }
.Lp0_dec_done_A2:
	v_readlane_b32 s4, v252, 15
	v_readlane_b32 s5, v252, 16
	s_add_u32 s20, s4, s12
	s_addc_u32 s21, s5, 0
	s_cmp_eq_u32 s26, 0
	s_cselect_b64 vcc, -1, 0
	v_mul_u32_u24_e32 v30, s18, v27
	v_cndmask_b32_e32 v35, v24, v23, vcc
	v_cndmask_b32_e32 v36, v26, v25, vcc
	v_add_u32_e32 v30, v30, v35
	v_mad_u32_u24 v31, v36, s27, v22
	global_load_dwordx4 v[104:107], v28, s[24:25]
	global_load_dwordx4 v[108:111], v28, s[24:25] offset:16
	global_load_dwordx4 v[112:115], v28, s[24:25] offset:128
	global_load_dwordx4 v[116:119], v28, s[24:25] offset:144
	global_load_dwordx4 v[40:43], v30, s[16:17]
	s_add_u32 s16, s16, s18
	s_addc_u32 s17, s17, 0
	global_load_dwordx4 v[44:47], v30, s[16:17]
	s_add_u32 s16, s16, s18
	s_addc_u32 s17, s17, 0
	global_load_dwordx4 v[48:51], v30, s[16:17]
	s_add_u32 s16, s16, s18
	s_addc_u32 s17, s17, 0
	global_load_dwordx4 v[52:55], v30, s[16:17]
	s_add_u32 s16, s16, s18
	s_addc_u32 s17, s17, 0
	global_load_dwordx4 v[56:59], v30, s[16:17]
	s_add_u32 s16, s16, s18
	s_addc_u32 s17, s17, 0
	global_load_dwordx4 v[60:63], v30, s[16:17]
	s_add_u32 s16, s16, s18
	s_addc_u32 s17, s17, 0
	global_load_dwordx4 v[64:67], v30, s[16:17]
	s_add_u32 s16, s16, s18
	s_addc_u32 s17, s17, 0
	global_load_dwordx4 v[68:71], v30, s[16:17]
	s_add_u32 s16, s16, s19
	s_addc_u32 s17, s17, 0
	global_load_dwordx4 v[72:75], v30, s[16:17]
	s_add_u32 s16, s16, s18
	s_addc_u32 s17, s17, 0
	global_load_dwordx4 v[76:79], v30, s[16:17]
	s_add_u32 s16, s16, s18
	s_addc_u32 s17, s17, 0
	global_load_dwordx4 v[80:83], v30, s[16:17]
	s_add_u32 s16, s16, s18
	s_addc_u32 s17, s17, 0
	global_load_dwordx4 v[84:87], v30, s[16:17]
	s_add_u32 s16, s16, s18
	s_addc_u32 s17, s17, 0
	global_load_dwordx4 v[88:91], v30, s[16:17]
	s_add_u32 s16, s16, s18
	s_addc_u32 s17, s17, 0
	global_load_dwordx4 v[92:95], v30, s[16:17]
	s_add_u32 s16, s16, s18
	s_addc_u32 s17, s17, 0
	global_load_dwordx4 v[96:99], v30, s[16:17]
	s_add_u32 s16, s16, s18
	s_addc_u32 s17, s17, 0
	global_load_dwordx4 v[100:103], v30, s[16:17]
	s_waitcnt vmcnt(28)
	s_branch .Lp0_go_a
.Lp0_last_a:
	s_waitcnt vmcnt(8)
.Lp0_go_a:
	s_cmp_eq_u32 s47, 0
	s_cbranch_scc1 .Lp0_nog_B1
	v_pk_mul_f32 v[120:121], v[120:121], v[184:185] op_sel_hi:[1,0]
	v_pk_mul_f32 v[122:123], v[122:123], v[184:185] op_sel_hi:[1,0]
	v_pk_mul_f32 v[124:125], v[124:125], v[184:185] op_sel:[0,1] op_sel_hi:[1,1]
	v_pk_mul_f32 v[126:127], v[126:127], v[184:185] op_sel:[0,1] op_sel_hi:[1,1]
	v_pk_mul_f32 v[128:129], v[128:129], v[186:187] op_sel_hi:[1,0]
	v_pk_mul_f32 v[130:131], v[130:131], v[186:187] op_sel_hi:[1,0]
	v_pk_mul_f32 v[132:133], v[132:133], v[186:187] op_sel:[0,1] op_sel_hi:[1,1]
	v_pk_mul_f32 v[134:135], v[134:135], v[186:187] op_sel:[0,1] op_sel_hi:[1,1]
	v_pk_mul_f32 v[136:137], v[136:137], v[188:189] op_sel_hi:[1,0]
	v_pk_mul_f32 v[138:139], v[138:139], v[188:189] op_sel_hi:[1,0]
	v_pk_mul_f32 v[140:141], v[140:141], v[188:189] op_sel:[0,1] op_sel_hi:[1,1]
	v_pk_mul_f32 v[142:143], v[142:143], v[188:189] op_sel:[0,1] op_sel_hi:[1,1]
	v_pk_mul_f32 v[144:145], v[144:145], v[190:191] op_sel_hi:[1,0]
	v_pk_mul_f32 v[146:147], v[146:147], v[190:191] op_sel_hi:[1,0]
	v_pk_mul_f32 v[148:149], v[148:149], v[190:191] op_sel:[0,1] op_sel_hi:[1,1]
	v_pk_mul_f32 v[150:151], v[150:151], v[190:191] op_sel:[0,1] op_sel_hi:[1,1]
	v_pk_mul_f32 v[152:153], v[152:153], v[192:193] op_sel_hi:[1,0]
	v_pk_mul_f32 v[154:155], v[154:155], v[192:193] op_sel_hi:[1,0]
	v_pk_mul_f32 v[156:157], v[156:157], v[192:193] op_sel:[0,1] op_sel_hi:[1,1]
	v_pk_mul_f32 v[158:159], v[158:159], v[192:193] op_sel:[0,1] op_sel_hi:[1,1]
	v_pk_mul_f32 v[160:161], v[160:161], v[194:195] op_sel_hi:[1,0]
	v_pk_mul_f32 v[162:163], v[162:163], v[194:195] op_sel_hi:[1,0]
	v_pk_mul_f32 v[164:165], v[164:165], v[194:195] op_sel:[0,1] op_sel_hi:[1,1]
	v_pk_mul_f32 v[166:167], v[166:167], v[194:195] op_sel:[0,1] op_sel_hi:[1,1]
	v_pk_mul_f32 v[168:169], v[168:169], v[196:197] op_sel_hi:[1,0]
	v_pk_mul_f32 v[170:171], v[170:171], v[196:197] op_sel_hi:[1,0]
	v_pk_mul_f32 v[172:173], v[172:173], v[196:197] op_sel:[0,1] op_sel_hi:[1,1]
	v_pk_mul_f32 v[174:175], v[174:175], v[196:197] op_sel:[0,1] op_sel_hi:[1,1]
	v_pk_mul_f32 v[176:177], v[176:177], v[198:199] op_sel_hi:[1,0]
	v_pk_mul_f32 v[178:179], v[178:179], v[198:199] op_sel_hi:[1,0]
	v_pk_mul_f32 v[180:181], v[180:181], v[198:199] op_sel:[0,1] op_sel_hi:[1,1]
	v_pk_mul_f32 v[182:183], v[182:183], v[198:199] op_sel:[0,1] op_sel_hi:[1,1]
; #define LAS __attribute__((address_space(3)))
; #define GAS1 __attribute__((address_space(1)))
; __device__ __forceinline__ unsigned pk2(float lo, float hi) { return pg8::cvt_pk_bf16(lo, hi); }
; __device__ __forceinline__ void p0_transpose_item(const float* W, int K, int N, bf16* WT, int item, bool inproj, const float* gk, LAS float* scr, int lane) {
;     ...
;     f32x4 g0 = (f32x4){1.f, 1.f, 1.f, 1.f}, g1 = g0;
;     if (gk) { g0 = *(const f32x4*)(gk + k0 + 8 * c); g1 = *(const f32x4*)(gk + k0 + 8 * c + 4); }
; #pragma unroll
;     for (int j = 0; j < 8; ++j) { const int n = (lane & 7) + 8 * j; const LAS float* s = scr + (8 * c) * 65 + n;
;         v4u o; o.x = pk2(s[0 * 65] * g0.x, s[1 * 65] * g0.y); o.y = pk2(s[2 * 65] * g0.z, s[3 * 65] * g0.w); o.z = pk2(s[4 * 65] * g1.x, s[5 * 65] * g1.y); o.w = pk2(s[6 * 65] * g1.z, s[7 * 65] * g1.w);
;         *(GAS1 v4u*)(WT + (size_t)(n0 + n) * K + k0 + 8 * c) = o; }
.Lp0_nog_B1:
	v_cvt_pk_bf16_f32 v208, v120, v124
	v_cvt_pk_bf16_f32 v209, v128, v132
	v_cvt_pk_bf16_f32 v210, v136, v140
	v_cvt_pk_bf16_f32 v211, v144, v148
	global_store_dwordx4 v33, v[208:211], s[44:45]
	v_cvt_pk_bf16_f32 v212, v152, v156
	v_cvt_pk_bf16_f32 v213, v160, v164
	v_cvt_pk_bf16_f32 v214, v168, v172
	v_cvt_pk_bf16_f32 v215, v176, v180
	global_store_dwordx4 v33, v[212:215], s[44:45] offset:64
	s_add_u32 s44, s44, s46
	s_addc_u32 s45, s45, 0
	v_cvt_pk_bf16_f32 v216, v121, v125
	v_cvt_pk_bf16_f32 v217, v129, v133
	v_cvt_pk_bf16_f32 v218, v137, v141
	v_cvt_pk_bf16_f32 v219, v145, v149
	global_store_dwordx4 v33, v[216:219], s[44:45]
	v_cvt_pk_bf16_f32 v220, v153, v157
	v_cvt_pk_bf16_f32 v221, v161, v165
	v_cvt_pk_bf16_f32 v222, v169, v173
	v_cvt_pk_bf16_f32 v223, v177, v181
	global_store_dwordx4 v33, v[220:223], s[44:45] offset:64
	s_add_u32 s44, s44, s46
	s_addc_u32 s45, s45, 0
	v_cvt_pk_bf16_f32 v224, v122, v126
	v_cvt_pk_bf16_f32 v225, v130, v134
	v_cvt_pk_bf16_f32 v226, v138, v142
	v_cvt_pk_bf16_f32 v227, v146, v150
	global_store_dwordx4 v33, v[224:227], s[44:45]
	v_cvt_pk_bf16_f32 v228, v154, v158
	v_cvt_pk_bf16_f32 v229, v162, v166
	v_cvt_pk_bf16_f32 v230, v170, v174
	v_cvt_pk_bf16_f32 v231, v178, v182
	global_store_dwordx4 v33, v[228:231], s[44:45] offset:64
	s_add_u32 s44, s44, s46
	s_addc_u32 s45, s45, 0
	v_cvt_pk_bf16_f32 v232, v123, v127
	v_cvt_pk_bf16_f32 v233, v131, v135
	v_cvt_pk_bf16_f32 v234, v139, v143
	v_cvt_pk_bf16_f32 v235, v147, v151
	global_store_dwordx4 v33, v[232:235], s[44:45]
	v_cvt_pk_bf16_f32 v236, v155, v159
	v_cvt_pk_bf16_f32 v237, v163, v167
	v_cvt_pk_bf16_f32 v238, v171, v175
	v_cvt_pk_bf16_f32 v239, v179, v183
	global_store_dwordx4 v33, v[236:239], s[44:45] offset:64
	s_cmp_eq_u32 s59, 0
	s_cbranch_scc1 .Lp0_done
	s_add_u32 s10, s10, s11
	s_cmp_lt_u32 s10, 23552
	s_cselect_b32 s59, 1, 0
	s_cbranch_scc0 .Lp0_last_b
	s_cmp_ge_u32 s10, 11776
	s_cselect_b32 s0, 1, 0
	s_cselect_b32 s1, 11776, 0
	s_sub_u32 s1, s10, s1
	s_lshl_b32 s7, s0, 13
	s_mov_b32 s50, 0
	s_cmp_lt_u32 s1, 2560
	s_cbranch_scc1 .Lp0_in_B3
	s_cmp_lt_u32 s1, 3584
	s_cbranch_scc1 .Lp0_out_B3
	s_cmp_lt_u32 s1, 7680
	s_cbranch_scc1 .Lp0_up_B3
	s_sub_u32 s1, s1, 7680
	s_and_b32 s4, s1, 7
	s_lshr_b32 s5, s1, 3
	s_lshr_b32 s2, s5, 2
	s_and_b32 s3, s5, 3
	s_lshl_b32 s2, s2, 0
	s_lshl_b32 s3, s3, 3
	s_lshr_b32 s5, s4, 3
	s_and_b32 s4, s4, 7
	s_add_u32 s2, s2, s5
	s_add_u32 s3, s3, s4
	v_readlane_b32 s4, v252, 9
	v_readlane_b32 s5, v252, 10
	s_mul_i32 s6, s0, 0x4000000
	s_mul_i32 s12, s2, 0x80000
	s_lshl_b32 s13, s3, 8
	s_add_u32 s12, s12, s13
	s_add_u32 s12, s12, s6
	s_add_u32 s40, s4, s12
	s_addc_u32 s41, s5, 0
	s_mov_b32 s42, 0x2000
	s_mov_b32 s43, 0x32000
	s_mul_i32 s6, s0, 0x2000000
	s_add_u32 s6, s6, 0x7800000
	s_lshl_b32 s12, s3, 20
	s_lshl_b32 s13, s2, 7
	s_add_u32 s12, s12, s13
	s_add_u32 s12, s12, s6
	s_mov_b32 s51, 0x4000
	s_mov_b32 s46, 0x4000
	s_mov_b32 s47, 0
	v_readlane_b32 s48, v252, 19
	v_readlane_b32 s49, v252, 20
	s_branch .Lp0_dec_done_B3

; #define LDS_WAIT() asm volatile("s_waitcnt lgkmcnt(0)" ::: "memory")
; __device__ __forceinline__ void p0_transpose_item(const float* W, int K, int N, bf16* WT, int item, bool inproj, const float* gk, LAS float* scr, int lane) {
;     ...
; #pragma unroll
;     for (int kk = 0; kk < 64; ++kk) tv[kk] = src[(size_t)kk * N];
; #pragma unroll
;     for (int kk = 0; kk < 64; ++kk) scr[kk * 65 + cl] = tv[kk];
;     LDS_WAIT(); asm volatile("" ::: "memory");
;     const int c = lane >> 3;
.Lp0_dec_done_B3:
	v_readlane_b32 s4, v252, 15
	v_readlane_b32 s5, v252, 16
	s_add_u32 s44, s4, s12
	s_addc_u32 s45, s5, 0
	s_cmp_eq_u32 s50, 0
	s_cselect_b64 vcc, -1, 0
	v_mul_u32_u24_e32 v32, s42, v27
	v_cndmask_b32_e32 v35, v24, v23, vcc
	v_cndmask_b32_e32 v36, v26, v25, vcc
	v_add_u32_e32 v32, v32, v35
	v_mad_u32_u24 v33, v36, s51, v22
	global_load_dwordx4 v[184:187], v28, s[48:49]
	global_load_dwordx4 v[188:191], v28, s[48:49] offset:16
	global_load_dwordx4 v[192:195], v28, s[48:49] offset:128
	global_load_dwordx4 v[196:199], v28, s[48:49] offset:144
	global_load_dwordx4 v[120:123], v32, s[40:41]
	s_add_u32 s40, s40, s42
	s_addc_u32 s41, s41, 0
	global_load_dwordx4 v[124:127], v32, s[40:41]
	s_add_u32 s40, s40, s42
	s_addc_u32 s41, s41, 0
	global_load_dwordx4 v[128:131], v32, s[40:41]
	s_add_u32 s40, s40, s42
	s_addc_u32 s41, s41, 0
	global_load_dwordx4 v[132:135], v32, s[40:41]
	s_add_u32 s40, s40, s42
	s_addc_u32 s41, s41, 0
	global_load_dwordx4 v[136:139], v32, s[40:41]
	s_add_u32 s40, s40, s42
	s_addc_u32 s41, s41, 0
	global_load_dwordx4 v[140:143], v32, s[40:41]
	s_add_u32 s40, s40, s42
	s_addc_u32 s41, s41, 0
	global_load_dwordx4 v[144:147], v32, s[40:41]
	s_add_u32 s40, s40, s42
	s_addc_u32 s41, s41, 0
	global_load_dwordx4 v[148:151], v32, s[40:41]
	s_add_u32 s40, s40, s43
	s_addc_u32 s41, s41, 0
	global_load_dwordx4 v[152:155], v32, s[40:41]
	s_add_u32 s40, s40, s42
	s_addc_u32 s41, s41, 0
	global_load_dwordx4 v[156:159], v32, s[40:41]
	s_add_u32 s40, s40, s42
	s_addc_u32 s41, s41, 0
	global_load_dwordx4 v[160:163], v32, s[40:41]
	s_add_u32 s40, s40, s42
	s_addc_u32 s41, s41, 0
	global_load_dwordx4 v[164:167], v32, s[40:41]
	s_add_u32 s40, s40, s42
	s_addc_u32 s41, s41, 0
	global_load_dwordx4 v[168:171], v32, s[40:41]
	s_add_u32 s40, s40, s42
	s_addc_u32 s41, s41, 0
	global_load_dwordx4 v[172:175], v32, s[40:41]
	s_add_u32 s40, s40, s42
	s_addc_u32 s41, s41, 0
	global_load_dwordx4 v[176:179], v32, s[40:41]
	s_add_u32 s40, s40, s42
	s_addc_u32 s41, s41, 0
	global_load_dwordx4 v[180:183], v32, s[40:41]
	s_waitcnt vmcnt(28)
	s_branch .Lp0_go_b

; #define LAS __attribute__((address_space(3)))
; #define GAS1 __attribute__((address_space(1)))
; __device__ __forceinline__ unsigned pk2(float lo, float hi) { return pg8::cvt_pk_bf16(lo, hi); }
; __device__ __forceinline__ void p0_transpose_item(const float* W, int K, int N, bf16* WT, int item, bool inproj, const float* gk, LAS float* scr, int lane) {
;     ...
;     for (int j = 0; j < 8; ++j) { const int n = (lane & 7) + 8 * j; const LAS float* s = scr + (8 * c) * 65 + n;
;         v4u o; o.x = pk2(s[0 * 65] * g0.x, s[1 * 65] * g0.y); o.y = pk2(s[2 * 65] * g0.z, s[3 * 65] * g0.w); o.z = pk2(s[4 * 65] * g1.x, s[5 * 65] * g1.y); o.w = pk2(s[6 * 65] * g1.z, s[7 * 65] * g1.w);
;         *(GAS1 v4u*)(WT + (size_t)(n0 + n) * K + k0 + 8 * c) = o; }
; __device__ __forceinline__ void rope_entry(int pos, int j, float& co, float& si) {
;     double f = 1.0; double rr = 0.8659643233600653; int e = j;
;     for (int b = 0; b < 6; ++b) { if (e & 1) f *= rr; rr *= rr; e >>= 1; }
;     const double x = (double)pos * f;
;     const double kq = __builtin_rint(x * 0.6366197723675814);
;     double r = __builtin_fma(-kq, 1.5707963267948966, x); r = __builtin_fma(-kq, 6.123233995736766e-17, r);
;     const double r2 = r * r;
;     double s = -1.0 / 1307674368000.0; s = s * r2 + 1.0 / 6227020800.0; s = s * r2 - 1.0 / 39916800.0; s = s * r2 + 1.0 / 362880.0; s = s * r2 - 1.0 / 5040.0; s = s * r2 + 1.0 / 120.0; s = s * r2 - 1.0 / 6.0; s = s * r2 * r + r;
;     double c = 1.0 / 20922789888000.0; c = c * r2 - 1.0 / 87178291200.0; c = c * r2 + 1.0 / 479001600.0; c = c * r2 - 1.0 / 3628800.0; c = c * r2 + 1.0 / 40320.0; c = c * r2 - 1.0 / 720.0; c = c * r2 + 1.0 / 24.0; c = c * r2 - 0.5; c = c * r2 + 1.0;
.Lp0_nog_A2:
	v_cvt_pk_bf16_f32 v208, v40, v44
	v_cvt_pk_bf16_f32 v209, v48, v52
	v_cvt_pk_bf16_f32 v210, v56, v60
	v_cvt_pk_bf16_f32 v211, v64, v68
	global_store_dwordx4 v31, v[208:211], s[20:21]
	v_cvt_pk_bf16_f32 v212, v72, v76
	v_cvt_pk_bf16_f32 v213, v80, v84
	v_cvt_pk_bf16_f32 v214, v88, v92
	v_cvt_pk_bf16_f32 v215, v96, v100
	global_store_dwordx4 v31, v[212:215], s[20:21] offset:64
	s_add_u32 s20, s20, s22
	s_addc_u32 s21, s21, 0
	v_cvt_pk_bf16_f32 v216, v41, v45
	v_cvt_pk_bf16_f32 v217, v49, v53
	v_cvt_pk_bf16_f32 v218, v57, v61
	v_cvt_pk_bf16_f32 v219, v65, v69
	global_store_dwordx4 v31, v[216:219], s[20:21]
	v_cvt_pk_bf16_f32 v220, v73, v77
	v_cvt_pk_bf16_f32 v221, v81, v85
	v_cvt_pk_bf16_f32 v222, v89, v93
	v_cvt_pk_bf16_f32 v223, v97, v101
	global_store_dwordx4 v31, v[220:223], s[20:21] offset:64
	s_add_u32 s20, s20, s22
	s_addc_u32 s21, s21, 0
	v_cvt_pk_bf16_f32 v224, v42, v46
	v_cvt_pk_bf16_f32 v225, v50, v54
	v_cvt_pk_bf16_f32 v226, v58, v62
	v_cvt_pk_bf16_f32 v227, v66, v70
	global_store_dwordx4 v31, v[224:227], s[20:21]
	v_cvt_pk_bf16_f32 v228, v74, v78
	v_cvt_pk_bf16_f32 v229, v82, v86
	v_cvt_pk_bf16_f32 v230, v90, v94
	v_cvt_pk_bf16_f32 v231, v98, v102
	global_store_dwordx4 v31, v[228:231], s[20:21] offset:64
	s_add_u32 s20, s20, s22
	s_addc_u32 s21, s21, 0
	v_cvt_pk_bf16_f32 v232, v43, v47
	v_cvt_pk_bf16_f32 v233, v51, v55
	v_cvt_pk_bf16_f32 v234, v59, v63
	v_cvt_pk_bf16_f32 v235, v67, v71
	global_store_dwordx4 v31, v[232:235], s[20:21]
	v_cvt_pk_bf16_f32 v236, v75, v79
	v_cvt_pk_bf16_f32 v237, v83, v87
	v_cvt_pk_bf16_f32 v238, v91, v95
	v_cvt_pk_bf16_f32 v239, v99, v103
	global_store_dwordx4 v31, v[236:239], s[20:21] offset:64
	s_cmp_eq_u32 s59, 0
	s_cbranch_scc0 .Lp0_loop
.Lp0_done:
.LBB0_36:
	s_lshl_b32 s0, s9, 6
	s_lshl_b32 s1, s94, 9
	s_add_i32 s0, s0, s1
	v_add_u32_e32 v2, s0, v10
	s_mov_b32 s0, 0x40000
	v_cmp_gt_i32_e32 vcc, s0, v2
	s_and_saveexec_b64 s[2:3], vcc
	v_readlane_b32 s40, v252, 13
	v_readlane_b32 s50, v252, 33
	v_readlane_b32 s42, v252, 15
	v_readlane_b32 s43, v252, 16
	v_readlane_b32 s51, v252, 34
	v_readlane_b32 s46, v252, 35
	v_readlane_b32 s41, v252, 14
	s_cbranch_execz .LBB0_45
	v_and_b32_e32 v1, 1, v10
	v_bfe_i32 v3, v10, 0, 1
	v_mov_b32_e32 v4, 0x3febb5fa
	v_mov_b32_e32 v5, 0x3ff00000
	v_cmp_eq_u32_e32 vcc, 0, v1
	s_mov_b32 s0, 0x24115d99
	s_mov_b32 s1, 0x3fe7ff22
	v_cndmask_b32_e32 v5, v4, v5, vcc
	v_and_b32_e32 v4, 0xd00ab22c, v3
	s_mov_b32 s12, 0x3c1c381d
	s_mov_b32 s14, 0x6248490c
	s_mov_b32 s16, 0x99999992
	s_mov_b32 s18, 0x47ae146f
	s_mov_b32 s20, 0x6dc9c883
	s_mov_b32 s22, 0x54442d18
	s_mov_b32 s24, 0x33145c07
	s_mov_b32 s26, 0xe733b81f
	v_mov_b32_e32 v20, 0x1a01a01a
	v_mov_b32_e32 v24, 0x55555555
	s_lshl_b32 s4, s50, 9
	v_mul_f64 v[6:7], v[4:5], s[0:1]
	v_lshlrev_b32_e32 v8, 1, v2
	s_lshl_b32 s5, s50, 10
	s_mov_b64 s[10:11], 0
	s_mov_b32 s13, 0x3fe1feb3
	s_mov_b32 s15, 0x3fd43d13
	s_mov_b32 s17, 0x3fb99999
	s_mov_b32 s19, 0x3f847ae1
	s_mov_b32 s21, 0x3fe45f30
	s_mov_b32 s23, 0xbff921fb
	s_mov_b32 s25, 0xbc91a626
	v_mov_b32_e32 v12, 0x13a86d09
	v_mov_b32_e32 v13, 0x3de61246
	s_mov_b32 s27, 0xbd6ae7f3
	v_mov_b32_e32 v14, 0x67f544e4
	v_mov_b32_e32 v15, 0xbe5ae645
	v_mov_b32_e32 v16, 0xa556c734
	v_mov_b32_e32 v17, 0x3ec71de3
	v_mov_b32_e32 v21, 0xbf2a01a0
	v_mov_b32_e32 v22, 0x11111111
	v_mov_b32_e32 v23, 0x3f811111
	v_mov_b32_e32 v25, 0xbfc55555
	v_mov_b32_e32 v26, 0xa8c07c9d
	v_mov_b32_e32 v27, 0xbda93974
	s_mov_b32 s29, 0x3d2ae7f3
	s_mov_b32 s28, s26
	v_mov_b32_e32 v28, 0xeff8d898
	v_mov_b32_e32 v29, 0x3e21eed8
	v_mov_b32_e32 v30, 0xb7789f5c
	v_mov_b32_e32 v31, 0xbe927e4f
	v_mov_b32_e32 v33, 0x3efa01a0
	v_mov_b32_e32 v32, v20
	v_mov_b32_e32 v34, 0x16c16c17
	v_mov_b32_e32 v35, 0xbf56c16c
	v_mov_b32_e32 v37, 0x3fa55555
	v_mov_b32_e32 v36, v24
	s_mov_b32 s9, 0x1fa00000
	s_mov_b32 s37, 0x3ffff
	v_mov_b32_e32 v1, v2
	s_branch .LBB0_40
